# final norm: loop-invariant final_g loads hoisted out of the row loop (no per-chunk vmcnt(0) round trips)
# speedup vs baseline: 1.0277x; 1.0019x over previous
; __device__ __forceinline__ int get_tid() { int t = threadIdx.x & 255; asm volatile("" : "+v"(t)); return t; }
; __device__ __forceinline__ int get_hb() { int t = __builtin_amdgcn_readfirstlane((int)(threadIdx.x >> 8)); asm volatile("" : "+s"(t)); return t; }
; __device__ __forceinline__ int get_rbid() { int t = blockIdx.x; asm volatile("" : "+s"(t)); return t; }
; __device__ __forceinline__ int get_bid() { return 2 * get_rbid() + get_hb(); }
; __device__ __forceinline__ void phase_final_norm(CP& p) {
;   const int lane = get_tid() & 63, wv = get_tid() >> 6;
;   for (int r = get_bid() * 4 + wv; r < 16384; r += VGRID * 4) {
;     const bf16_t* srow = p.X16 + (size_t)r * 1024;
;     float* row = p.X + (size_t)r * 1024;
;     f32x4 v[4]; float ss = 0.f;
; #pragma unroll
;     for (int i = 0; i < 4; ++i) { v[i] = ld4_bf16(srow + lane * 4 + 256 * i); ss += v[i][0] * v[i][0] + v[i][1] * v[i][1] + v[i][2] * v[i][2] + v[i][3] * v[i][3]; }
;     ss = wave_sum(ss);
;     const float rr = rsqrtf(ss * (1.0f / 1024.0f) + 1e-6f);
; #pragma unroll
;     for (int i = 0; i < 4; ++i) {
;       const int k = lane * 4 + 256 * i;
;       const f32x4 g4 = *(const f32x4*)(p.final_g + k);
;       f32x4 o; o[0] = v[i][0] * rr * g4[0]; o[1] = v[i][1] * rr * g4[1]; o[2] = v[i][2] * rr * g4[2]; o[3] = v[i][3] * rr * g4[3];
;       __builtin_nontemporal_store(o, (f32x4*)(row + k));
;     }
;   }
; __global__ void __launch_bounds__(512, 2) mega(P p_arg) {
;     ...
;   if (ph0 <= 18 && 18 < ph1) {
;     asm volatile("" : "+s"(pp));
;     CP& p = *pp;
;     const int bid = get_rbid();
;     const int vid0 = (G & 7) ? bid : ((bid & 7) * (G >> 3) + (bid >> 3));
;     const int hb = get_hb();
;     char* smem_h = smem + hb * HALF_LDS; (void)smem_h;
;     const float* mv0 = p.modv; const float* mv1 = p.modv + (size_t)9 * 6144;
;     (void)mv0; (void)mv1; (void)vid0;
;     phase_final_norm(p);
.LBB0_3649:
	s_cmp_lt_i32 s52, 19
	s_cselect_b64 s[4:5], -1, 0
	s_cmp_gt_i32 s53, 18
	s_cselect_b64 s[6:7], -1, 0
	s_and_b64 s[4:5], s[4:5], s[6:7]
	s_andn2_b64 vcc, exec, s[4:5]
	s_cbranch_vccnz .LBB0_3721
	s_mov_b32 s3, s2
	v_and_b32_e32 v2, 0xff, v1
	v_readfirstlane_b32 s3, v1
	s_lshr_b32 s3, s3, 8
	s_mov_b32 s4, s3
	v_mov_b32_e32 v6, v2
	s_lshl_b32 s2, s2, 3
	s_lshl_b32 s3, s3, 2
	v_ashrrev_i32_e32 v2, 6, v2
	s_add_i32 s3, s3, s2
	v_add_u32_e32 v2, s3, v2
	s_movk_i32 s2, 0x4000
	v_cmp_gt_i32_e32 vcc, s2, v2
	s_and_saveexec_b64 s[2:3], vcc
	s_cbranch_execz .LBB0_3653
	v_mbcnt_lo_u32_b32 v3, -1, 0
	v_mbcnt_hi_u32_b32 v3, -1, v3
	v_and_b32_e32 v4, 64, v3
	v_add_u32_e32 v4, 64, v4
	v_xor_b32_e32 v5, 32, v3
	v_cmp_lt_i32_e32 vcc, v5, v4
	s_load_dwordx2 s[8:9], s[0:1], 0x1c0
	s_load_dwordx4 s[4:7], s[0:1], 0x118
	v_cndmask_b32_e32 v5, v3, v5, vcc
	v_lshlrev_b32_e32 v10, 2, v5
	v_xor_b32_e32 v5, 16, v3
	v_cmp_lt_i32_e32 vcc, v5, v4
	v_and_b32_e32 v16, 63, v6
	s_lshl_b32 s0, s54, 3
	v_cndmask_b32_e32 v5, v3, v5, vcc
	v_lshlrev_b32_e32 v11, 2, v5
	v_xor_b32_e32 v5, 8, v3
	v_cmp_lt_i32_e32 vcc, v5, v4
	s_ashr_i32 s1, s0, 31
	s_movk_i32 s10, 0x3fff
	v_cndmask_b32_e32 v5, v3, v5, vcc
	v_lshlrev_b32_e32 v12, 2, v5
	v_xor_b32_e32 v5, 4, v3
	v_cmp_lt_i32_e32 vcc, v5, v4
	s_nop 1
	v_cndmask_b32_e32 v5, v3, v5, vcc
	v_lshlrev_b32_e32 v13, 2, v5
	v_xor_b32_e32 v5, 2, v3
	v_cmp_lt_i32_e32 vcc, v5, v4
	s_nop 1
	v_cndmask_b32_e32 v5, v3, v5, vcc
	v_lshlrev_b32_e32 v14, 2, v5
	v_xor_b32_e32 v5, 1, v3
	v_cmp_lt_i32_e32 vcc, v5, v4
	s_nop 1
	v_cndmask_b32_e32 v3, v3, v5, vcc
	v_lshlrev_b32_e32 v15, 2, v3
	v_lshlrev_b32_e32 v3, 4, v6
	v_and_b32_e32 v4, 0x3f0, v3
	v_ashrrev_i32_e32 v3, 31, v2
	v_lshlrev_b64 v[8:9], 11, v[2:3]
	v_lshl_or_b32 v8, v16, 3, v8
	s_waitcnt lgkmcnt(0)
	v_lshl_add_u64 v[6:7], s[8:9], 0, v[8:9]
	v_lshlrev_b64 v[8:9], 12, v[2:3]
	v_mov_b32_e32 v5, 0
	v_lshl_or_b32 v8, v16, 4, v8
	v_lshl_add_u64 v[4:5], s[4:5], 0, v[4:5]
	s_mov_b64 s[4:5], 0x604
	v_lshl_add_u64 v[8:9], s[6:7], 0, v[8:9]
	s_mov_b64 s[6:7], 0xc00
	v_lshl_add_u64 v[6:7], v[6:7], 0, s[4:5]
	s_lshl_b64 s[4:5], s[0:1], 11
	v_lshl_add_u64 v[8:9], v[8:9], 0, s[6:7]
	s_lshl_b64 s[6:7], s[0:1], 12
	s_mov_b64 s[8:9], 0
	v_mov_b32_e32 v3, 0x358637bd
	s_mov_b32 s1, 0x800000
	global_load_dwordx4 v[48:51], v[4:5], off
	global_load_dwordx4 v[52:55], v[4:5], off offset:1024
	global_load_dwordx4 v[56:59], v[4:5], off offset:2048
	global_load_dwordx4 v[60:63], v[4:5], off offset:3072
	s_waitcnt vmcnt(0)
.LBB0_3652:
	global_load_dwordx2 v[20:21], v[6:7], off offset:-1540
	global_load_dwordx2 v[22:23], v[6:7], off offset:-1028
	global_load_dwordx2 v[24:25], v[6:7], off offset:-516
	global_load_dwordx2 v[26:27], v[6:7], off offset:-4
	v_add_u32_e32 v2, s0, v2
	v_lshl_add_u64 v[6:7], v[6:7], 0, s[4:5]
	s_waitcnt vmcnt(3)
	v_and_b32_e32 v29, 0xffff0000, v20
	v_lshlrev_b32_e32 v28, 16, v20
	s_waitcnt vmcnt(2)
	v_and_b32_e32 v33, 0xffff0000, v22
	s_waitcnt vmcnt(1)
	v_and_b32_e32 v37, 0xffff0000, v24
	v_mov_b32_e32 v32, v29
	v_lshlrev_b32_e32 v20, 16, v21
	v_lshlrev_b32_e32 v31, 16, v22
	v_lshlrev_b32_e32 v36, 16, v24
	s_waitcnt vmcnt(0)
	v_and_b32_e32 v41, 0xffff0000, v26
	v_mov_b32_e32 v30, v28
	v_mov_b32_e32 v40, v37
	v_pk_mul_f32 v[44:45], v[32:33], v[32:33]
	v_and_b32_e32 v21, 0xffff0000, v21
	v_lshlrev_b32_e32 v35, 16, v23
	v_lshlrev_b32_e32 v24, 16, v25
	v_lshlrev_b32_e32 v39, 16, v26
	v_mov_b32_e32 v34, v20
	v_mov_b32_e32 v38, v36
	v_pk_mul_f32 v[46:47], v[40:41], v[40:41]
	v_pk_fma_f32 v[44:45], v[30:31], v[30:31], v[44:45]
	v_and_b32_e32 v23, 0xffff0000, v23
	v_and_b32_e32 v25, 0xffff0000, v25
	v_lshlrev_b32_e32 v43, 16, v27
	v_mov_b32_e32 v22, v21
	v_mov_b32_e32 v42, v24
	v_pk_fma_f32 v[46:47], v[38:39], v[38:39], v[46:47]
	v_pk_fma_f32 v[44:45], v[34:35], v[34:35], v[44:45]
	v_and_b32_e32 v27, 0xffff0000, v27
	v_mov_b32_e32 v26, v25
	v_pk_fma_f32 v[46:47], v[42:43], v[42:43], v[46:47]
	v_pk_fma_f32 v[44:45], v[22:23], v[22:23], v[44:45]
	v_pk_fma_f32 v[46:47], v[26:27], v[26:27], v[46:47]
	v_add_f32_e32 v22, v44, v45
	v_add_f32_e32 v22, v22, v46
	v_add_f32_e32 v22, v22, v47
	ds_bpermute_b32 v26, v10, v22
	v_mov_b32_e32 v32, v31
	v_mov_b32_e32 v40, v39
	s_waitcnt lgkmcnt(0)
	v_add_f32_e32 v22, v22, v26
	ds_bpermute_b32 v26, v11, v22
	s_waitcnt lgkmcnt(0)
	v_add_f32_e32 v22, v22, v26
	ds_bpermute_b32 v26, v12, v22
	s_waitcnt lgkmcnt(0)
	v_add_f32_e32 v22, v22, v26
	ds_bpermute_b32 v26, v13, v22
	s_waitcnt lgkmcnt(0)
	v_add_f32_e32 v22, v22, v26
	ds_bpermute_b32 v26, v14, v22
	s_waitcnt lgkmcnt(0)
	v_add_f32_e32 v22, v22, v26
	ds_bpermute_b32 v26, v15, v22
	s_waitcnt lgkmcnt(0)
	v_add_f32_e32 v22, v22, v26
	v_fmamk_f32 v22, v22, 0x3a800000, v3
	v_mul_f32_e32 v26, 0x4b800000, v22
	v_cmp_gt_f32_e32 vcc, s1, v22
	s_nop 1
	v_cndmask_b32_e32 v22, v22, v26, vcc
	v_rsq_f32_e32 v22, v22
	s_nop 0
	v_mul_f32_e32 v26, 0x45800000, v22
	v_cndmask_b32_e32 v30, v22, v26, vcc
	v_pk_mul_f32 v[28:29], v[30:31], v[28:29] op_sel_hi:[0,1]
	v_pk_mul_f32 v[20:21], v[30:31], v[20:21] op_sel_hi:[0,1]
	v_pk_mul_f32 v[18:19], v[50:51], v[20:21]
	v_pk_mul_f32 v[16:17], v[48:49], v[28:29]
	global_store_dwordx4 v[8:9], v[16:19], off offset:-3072 nt
	v_mov_b32_e32 v22, v35
	v_pk_mul_f32 v[20:21], v[30:31], v[22:23] op_sel_hi:[0,1]
	v_pk_mul_f32 v[22:23], v[30:31], v[32:33] op_sel_hi:[0,1]
	v_mov_b32_e32 v26, v43
	v_cmp_lt_i32_e32 vcc, s10, v2
	s_or_b64 s[8:9], vcc, s[8:9]
	v_pk_mul_f32 v[16:17], v[52:53], v[22:23]
	v_pk_mul_f32 v[18:19], v[54:55], v[20:21]
	global_store_dwordx4 v[8:9], v[16:19], off offset:-2048 nt
	v_pk_mul_f32 v[20:21], v[30:31], v[24:25] op_sel_hi:[0,1]
	v_pk_mul_f32 v[22:23], v[30:31], v[36:37] op_sel_hi:[0,1]
	v_pk_mul_f32 v[16:17], v[56:57], v[22:23]
	v_pk_mul_f32 v[18:19], v[58:59], v[20:21]
	global_store_dwordx4 v[8:9], v[16:19], off offset:-1024 nt
	v_pk_mul_f32 v[20:21], v[30:31], v[26:27] op_sel_hi:[0,1]
	v_pk_mul_f32 v[22:23], v[30:31], v[40:41] op_sel_hi:[0,1]
	v_pk_mul_f32 v[16:17], v[60:61], v[22:23]
	v_pk_mul_f32 v[18:19], v[62:63], v[20:21]
	global_store_dwordx4 v[8:9], v[16:19], off nt
	v_lshl_add_u64 v[8:9], v[8:9], 0, s[6:7]
	s_andn2_b64 exec, exec, s[8:9]
	s_cbranch_execnz .LBB0_3652
